# conv output stores write-through (sc1): whole-row 1 KiB stores, leaves L2 clean for the phase 6->7 barrier release
# speedup vs baseline: 1.0007x; 1.0007x over previous
; __device__ __forceinline__ float silu(float x) { return x * __builtin_amdgcn_rcpf(1.0f + __expf(-x)); }
; __device__ void phase_conv(const Params& p, unsigned char* smem, const int rep) {
;     ...
;         const bool samp = row >= NPROMPT;
;         const int t = samp ? ((row - NPROMPT) & 7) : (row & 2047);
;         const int b = samp ? ((row - NPROMPT) >> 3) : (row >> 11);
;         if (r == 0 || t == 0) {
; #pragma unroll
;           for (int k = 1; k <= 3; ++k) {
;             float hv[8];
;             if (t - k >= 0) {
;               unpack8(*(const u32x4*)(proj + (size_t)(row - k) * PROJ_LD + 2048 + ch0), hv);
;             } else if (samp) {
;               const float* sp = p.state_conv + ((size_t)b * 3 + (t - k + 3)) * 4096 + ch0;
;               const float4 s0 = *(const float4*)sp, s1 = *(const float4*)(sp + 4);
;               hv[0] = s0.x; hv[1] = s0.y; hv[2] = s0.z; hv[3] = s0.w; hv[4] = s1.x; hv[5] = s1.y; hv[6] = s1.z; hv[7] = s1.w;
;             } else {
; #pragma unroll
;               for (int q = 0; q < 8; ++q) hv[q] = 0.f;
;     ...
;         float xc[8], o[8];
;         unpack8(cur[q4], xc);
; #pragma unroll
;         for (int q = 0; q < 8; ++q) {
;           const float a = bs[q] + hm3[q] * wgt[0][q] + hm2[q] * wgt[1][q] + hm1[q] * wgt[2][q] + xc[q] * wgt[3][q];
;           o[q] = silu(a);
;           hm3[q] = hm2[q]; hm2[q] = hm1[q]; hm1[q] = xc[q];
;         }
;         u32x4 ov;
;         ov.x = pack2(o[0], o[1]); ov.y = pack2(o[2], o[3]); ov.z = pack2(o[4], o[5]); ov.w = pack2(o[6], o[7]);
;         *(u32x4*)(xbcc + (size_t)row * 4096 + ch0) = ov;
.Lcv_a0_x:
	v_lshlrev_b32_e32 v144, 16, v112
	v_and_b32_e32 v145, 0xffff0000, v112
	v_lshlrev_b32_e32 v146, 16, v113
	v_and_b32_e32 v147, 0xffff0000, v113
	v_lshlrev_b32_e32 v148, 16, v114
	v_and_b32_e32 v149, 0xffff0000, v114
	v_lshlrev_b32_e32 v150, 16, v115
	v_and_b32_e32 v151, 0xffff0000, v115
	v_pk_fma_f32 v[176:177], v[32:33], v[152:153], v[36:37]
	v_pk_fma_f32 v[178:179], v[34:35], v[154:155], v[38:39]
	v_pk_fma_f32 v[180:181], v[24:25], v[156:157], v[28:29]
	v_pk_fma_f32 v[182:183], v[26:27], v[158:159], v[30:31]
	v_pk_fma_f32 v[176:177], v[16:17], v[160:161], v[176:177]
	v_pk_fma_f32 v[178:179], v[18:19], v[162:163], v[178:179]
	v_pk_fma_f32 v[180:181], v[0:1], v[164:165], v[180:181]
	v_pk_fma_f32 v[182:183], v[2:3], v[166:167], v[182:183]
	v_pk_fma_f32 v[176:177], v[8:9], v[168:169], v[176:177]
	v_pk_fma_f32 v[178:179], v[10:11], v[170:171], v[178:179]
	v_pk_fma_f32 v[180:181], v[4:5], v[172:173], v[180:181]
	v_pk_fma_f32 v[182:183], v[6:7], v[174:175], v[182:183]
	v_pk_fma_f32 v[176:177], v[12:13], v[144:145], v[176:177]
	v_pk_fma_f32 v[178:179], v[14:15], v[146:147], v[178:179]
	v_pk_fma_f32 v[180:181], v[20:21], v[148:149], v[180:181]
	v_pk_fma_f32 v[182:183], v[22:23], v[150:151], v[182:183]
	v_pk_mul_f32 v[184:185], v[176:177], v[220:221]
	v_pk_mul_f32 v[186:187], v[178:179], v[220:221]
	v_pk_mul_f32 v[188:189], v[180:181], v[220:221]
	v_pk_mul_f32 v[190:191], v[182:183], v[220:221]
	v_exp_f32_e32 v184, v184
	v_exp_f32_e32 v185, v185
	v_exp_f32_e32 v186, v186
	v_exp_f32_e32 v187, v187
	v_exp_f32_e32 v188, v188
	v_exp_f32_e32 v189, v189
	v_exp_f32_e32 v190, v190
	v_exp_f32_e32 v191, v191
	v_pk_add_f32 v[184:185], v[184:185], v[222:223]
	v_pk_add_f32 v[186:187], v[186:187], v[222:223]
	v_pk_add_f32 v[188:189], v[188:189], v[222:223]
	v_pk_add_f32 v[190:191], v[190:191], v[222:223]
	v_rcp_f32_e32 v184, v184
	v_rcp_f32_e32 v185, v185
	v_rcp_f32_e32 v186, v186
	v_rcp_f32_e32 v187, v187
	v_rcp_f32_e32 v188, v188
	v_rcp_f32_e32 v189, v189
	v_rcp_f32_e32 v190, v190
	v_rcp_f32_e32 v191, v191
	v_pk_mul_f32 v[184:185], v[176:177], v[184:185]
	v_pk_mul_f32 v[186:187], v[178:179], v[186:187]
	v_pk_mul_f32 v[188:189], v[180:181], v[188:189]
	v_pk_mul_f32 v[190:191], v[182:183], v[190:191]
	v_cvt_pk_bf16_f32 v192, v184, v185
	v_cvt_pk_bf16_f32 v193, v186, v187
	v_cvt_pk_bf16_f32 v194, v188, v189
	v_cvt_pk_bf16_f32 v195, v190, v191
	global_store_dwordx4 v108, v[192:195], s[52:53] sc1
	v_add_u32_e32 v108, 0x2000, v108
	s_add_i32 s56, s56, 1
	s_waitcnt vmcnt(11)
	s_cmp_lt_u32 s56, 0x4000
	s_cselect_b32 s57, 0x7ff, 7
	s_and_b32 s57, s56, s57
	s_cmp_eq_u32 s57, 0
	s_cbranch_scc0 .Lcv_a1_x
	s_cmp_lt_u32 s56, 0x4000
	s_cbranch_scc0 .Lcv_a1_s
	v_mov_b32_e32 v160, 0
	v_mov_b32_e32 v161, 0
	v_mov_b32_e32 v162, 0
	v_mov_b32_e32 v163, 0
	v_mov_b32_e32 v164, 0
	v_mov_b32_e32 v165, 0
	v_mov_b32_e32 v166, 0
	v_mov_b32_e32 v167, 0
	v_mov_b32_e32 v168, 0
	v_mov_b32_e32 v169, 0
	v_mov_b32_e32 v170, 0
	v_mov_b32_e32 v171, 0
	v_mov_b32_e32 v172, 0
	v_mov_b32_e32 v173, 0
	v_mov_b32_e32 v174, 0
	v_mov_b32_e32 v175, 0
	v_mov_b32_e32 v144, 0
	v_mov_b32_e32 v145, 0
	v_mov_b32_e32 v146, 0
	v_mov_b32_e32 v147, 0
	v_mov_b32_e32 v148, 0
	v_mov_b32_e32 v149, 0
	v_mov_b32_e32 v150, 0
	v_mov_b32_e32 v151, 0
	s_branch .Lcv_a1_x

; __device__ __forceinline__ float silu(float x) { return x * __builtin_amdgcn_rcpf(1.0f + __expf(-x)); }
; __device__ void phase_conv(const Params& p, unsigned char* smem, const int rep) {
;     ...
;         const bool samp = row >= NPROMPT;
;         const int t = samp ? ((row - NPROMPT) & 7) : (row & 2047);
;         const int b = samp ? ((row - NPROMPT) >> 3) : (row >> 11);
;         if (r == 0 || t == 0) {
; #pragma unroll
;           for (int k = 1; k <= 3; ++k) {
;             float hv[8];
;             if (t - k >= 0) {
;               unpack8(*(const u32x4*)(proj + (size_t)(row - k) * PROJ_LD + 2048 + ch0), hv);
;             } else if (samp) {
;               const float* sp = p.state_conv + ((size_t)b * 3 + (t - k + 3)) * 4096 + ch0;
;               const float4 s0 = *(const float4*)sp, s1 = *(const float4*)(sp + 4);
;               hv[0] = s0.x; hv[1] = s0.y; hv[2] = s0.z; hv[3] = s0.w; hv[4] = s1.x; hv[5] = s1.y; hv[6] = s1.z; hv[7] = s1.w;
;             } else {
; #pragma unroll
;               for (int q = 0; q < 8; ++q) hv[q] = 0.f;
;     ...
;         float xc[8], o[8];
;         unpack8(cur[q4], xc);
; #pragma unroll
;         for (int q = 0; q < 8; ++q) {
;           const float a = bs[q] + hm3[q] * wgt[0][q] + hm2[q] * wgt[1][q] + hm1[q] * wgt[2][q] + xc[q] * wgt[3][q];
;           o[q] = silu(a);
;           hm3[q] = hm2[q]; hm2[q] = hm1[q]; hm1[q] = xc[q];
;         }
;         u32x4 ov;
;         ov.x = pack2(o[0], o[1]); ov.y = pack2(o[2], o[3]); ov.z = pack2(o[4], o[5]); ov.w = pack2(o[6], o[7]);
;         *(u32x4*)(xbcc + (size_t)row * 4096 + ch0) = ov;
.Lcv_a1_x:
	v_lshlrev_b32_e32 v152, 16, v116
	v_and_b32_e32 v153, 0xffff0000, v116
	v_lshlrev_b32_e32 v154, 16, v117
	v_and_b32_e32 v155, 0xffff0000, v117
	v_lshlrev_b32_e32 v156, 16, v118
	v_and_b32_e32 v157, 0xffff0000, v118
	v_lshlrev_b32_e32 v158, 16, v119
	v_and_b32_e32 v159, 0xffff0000, v119
	v_pk_fma_f32 v[176:177], v[32:33], v[160:161], v[36:37]
	v_pk_fma_f32 v[178:179], v[34:35], v[162:163], v[38:39]
	v_pk_fma_f32 v[180:181], v[24:25], v[164:165], v[28:29]
	v_pk_fma_f32 v[182:183], v[26:27], v[166:167], v[30:31]
	v_pk_fma_f32 v[176:177], v[16:17], v[168:169], v[176:177]
	v_pk_fma_f32 v[178:179], v[18:19], v[170:171], v[178:179]
	v_pk_fma_f32 v[180:181], v[0:1], v[172:173], v[180:181]
	v_pk_fma_f32 v[182:183], v[2:3], v[174:175], v[182:183]
	v_pk_fma_f32 v[176:177], v[8:9], v[144:145], v[176:177]
	v_pk_fma_f32 v[178:179], v[10:11], v[146:147], v[178:179]
	v_pk_fma_f32 v[180:181], v[4:5], v[148:149], v[180:181]
	v_pk_fma_f32 v[182:183], v[6:7], v[150:151], v[182:183]
	v_pk_fma_f32 v[176:177], v[12:13], v[152:153], v[176:177]
	v_pk_fma_f32 v[178:179], v[14:15], v[154:155], v[178:179]
	v_pk_fma_f32 v[180:181], v[20:21], v[156:157], v[180:181]
	v_pk_fma_f32 v[182:183], v[22:23], v[158:159], v[182:183]
	v_pk_mul_f32 v[184:185], v[176:177], v[220:221]
	v_pk_mul_f32 v[186:187], v[178:179], v[220:221]
	v_pk_mul_f32 v[188:189], v[180:181], v[220:221]
	v_pk_mul_f32 v[190:191], v[182:183], v[220:221]
	v_exp_f32_e32 v184, v184
	v_exp_f32_e32 v185, v185
	v_exp_f32_e32 v186, v186
	v_exp_f32_e32 v187, v187
	v_exp_f32_e32 v188, v188
	v_exp_f32_e32 v189, v189
	v_exp_f32_e32 v190, v190
	v_exp_f32_e32 v191, v191
	v_pk_add_f32 v[184:185], v[184:185], v[222:223]
	v_pk_add_f32 v[186:187], v[186:187], v[222:223]
	v_pk_add_f32 v[188:189], v[188:189], v[222:223]
	v_pk_add_f32 v[190:191], v[190:191], v[222:223]
	v_rcp_f32_e32 v184, v184
	v_rcp_f32_e32 v185, v185
	v_rcp_f32_e32 v186, v186
	v_rcp_f32_e32 v187, v187
	v_rcp_f32_e32 v188, v188
	v_rcp_f32_e32 v189, v189
	v_rcp_f32_e32 v190, v190
	v_rcp_f32_e32 v191, v191
	v_pk_mul_f32 v[184:185], v[176:177], v[184:185]
	v_pk_mul_f32 v[186:187], v[178:179], v[186:187]
	v_pk_mul_f32 v[188:189], v[180:181], v[188:189]
	v_pk_mul_f32 v[190:191], v[182:183], v[190:191]
	v_cvt_pk_bf16_f32 v192, v184, v185
	v_cvt_pk_bf16_f32 v193, v186, v187
	v_cvt_pk_bf16_f32 v194, v188, v189
	v_cvt_pk_bf16_f32 v195, v190, v191
	global_store_dwordx4 v108, v[192:195], s[52:53] sc1
	v_add_u32_e32 v108, 0x2000, v108
	s_add_i32 s56, s56, 1
	s_waitcnt vmcnt(11)
	s_cmp_lt_u32 s56, 0x4000
	s_cselect_b32 s57, 0x7ff, 7
	s_and_b32 s57, s56, s57
	s_cmp_eq_u32 s57, 0
	s_cbranch_scc0 .Lcv_a2_x
	s_cmp_lt_u32 s56, 0x4000
	s_cbranch_scc0 .Lcv_a2_s
	v_mov_b32_e32 v168, 0
	v_mov_b32_e32 v169, 0
	v_mov_b32_e32 v170, 0
	v_mov_b32_e32 v171, 0
	v_mov_b32_e32 v172, 0
	v_mov_b32_e32 v173, 0
	v_mov_b32_e32 v174, 0
	v_mov_b32_e32 v175, 0
	v_mov_b32_e32 v144, 0
	v_mov_b32_e32 v145, 0
	v_mov_b32_e32 v146, 0
	v_mov_b32_e32 v147, 0
	v_mov_b32_e32 v148, 0
	v_mov_b32_e32 v149, 0
	v_mov_b32_e32 v150, 0
	v_mov_b32_e32 v151, 0
	v_mov_b32_e32 v152, 0
	v_mov_b32_e32 v153, 0
	v_mov_b32_e32 v154, 0
	v_mov_b32_e32 v155, 0
	v_mov_b32_e32 v156, 0
	v_mov_b32_e32 v157, 0
	v_mov_b32_e32 v158, 0
	v_mov_b32_e32 v159, 0
	s_branch .Lcv_a2_x

; __device__ __forceinline__ float silu(float x) { return x * __builtin_amdgcn_rcpf(1.0f + __expf(-x)); }
; __device__ void phase_conv(const Params& p, unsigned char* smem, const int rep) {
;     ...
;         const bool samp = row >= NPROMPT;
;         const int t = samp ? ((row - NPROMPT) & 7) : (row & 2047);
;         const int b = samp ? ((row - NPROMPT) >> 3) : (row >> 11);
;         if (r == 0 || t == 0) {
; #pragma unroll
;           for (int k = 1; k <= 3; ++k) {
;             float hv[8];
;             if (t - k >= 0) {
;               unpack8(*(const u32x4*)(proj + (size_t)(row - k) * PROJ_LD + 2048 + ch0), hv);
;             } else if (samp) {
;               const float* sp = p.state_conv + ((size_t)b * 3 + (t - k + 3)) * 4096 + ch0;
;               const float4 s0 = *(const float4*)sp, s1 = *(const float4*)(sp + 4);
;               hv[0] = s0.x; hv[1] = s0.y; hv[2] = s0.z; hv[3] = s0.w; hv[4] = s1.x; hv[5] = s1.y; hv[6] = s1.z; hv[7] = s1.w;
;             } else {
; #pragma unroll
;               for (int q = 0; q < 8; ++q) hv[q] = 0.f;
;     ...
;         float xc[8], o[8];
;         unpack8(cur[q4], xc);
; #pragma unroll
;         for (int q = 0; q < 8; ++q) {
;           const float a = bs[q] + hm3[q] * wgt[0][q] + hm2[q] * wgt[1][q] + hm1[q] * wgt[2][q] + xc[q] * wgt[3][q];
;           o[q] = silu(a);
;           hm3[q] = hm2[q]; hm2[q] = hm1[q]; hm1[q] = xc[q];
;         }
;         u32x4 ov;
;         ov.x = pack2(o[0], o[1]); ov.y = pack2(o[2], o[3]); ov.z = pack2(o[4], o[5]); ov.w = pack2(o[6], o[7]);
;         *(u32x4*)(xbcc + (size_t)row * 4096 + ch0) = ov;
.Lcv_a2_x:
	v_lshlrev_b32_e32 v160, 16, v120
	v_and_b32_e32 v161, 0xffff0000, v120
	v_lshlrev_b32_e32 v162, 16, v121
	v_and_b32_e32 v163, 0xffff0000, v121
	v_lshlrev_b32_e32 v164, 16, v122
	v_and_b32_e32 v165, 0xffff0000, v122
	v_lshlrev_b32_e32 v166, 16, v123
	v_and_b32_e32 v167, 0xffff0000, v123
	v_pk_fma_f32 v[176:177], v[32:33], v[168:169], v[36:37]
	v_pk_fma_f32 v[178:179], v[34:35], v[170:171], v[38:39]
	v_pk_fma_f32 v[180:181], v[24:25], v[172:173], v[28:29]
	v_pk_fma_f32 v[182:183], v[26:27], v[174:175], v[30:31]
	v_pk_fma_f32 v[176:177], v[16:17], v[144:145], v[176:177]
	v_pk_fma_f32 v[178:179], v[18:19], v[146:147], v[178:179]
	v_pk_fma_f32 v[180:181], v[0:1], v[148:149], v[180:181]
	v_pk_fma_f32 v[182:183], v[2:3], v[150:151], v[182:183]
	v_pk_fma_f32 v[176:177], v[8:9], v[152:153], v[176:177]
	v_pk_fma_f32 v[178:179], v[10:11], v[154:155], v[178:179]
	v_pk_fma_f32 v[180:181], v[4:5], v[156:157], v[180:181]
	v_pk_fma_f32 v[182:183], v[6:7], v[158:159], v[182:183]
	v_pk_fma_f32 v[176:177], v[12:13], v[160:161], v[176:177]
	v_pk_fma_f32 v[178:179], v[14:15], v[162:163], v[178:179]
	v_pk_fma_f32 v[180:181], v[20:21], v[164:165], v[180:181]
	v_pk_fma_f32 v[182:183], v[22:23], v[166:167], v[182:183]
	v_pk_mul_f32 v[184:185], v[176:177], v[220:221]
	v_pk_mul_f32 v[186:187], v[178:179], v[220:221]
	v_pk_mul_f32 v[188:189], v[180:181], v[220:221]
	v_pk_mul_f32 v[190:191], v[182:183], v[220:221]
	v_exp_f32_e32 v184, v184
	v_exp_f32_e32 v185, v185
	v_exp_f32_e32 v186, v186
	v_exp_f32_e32 v187, v187
	v_exp_f32_e32 v188, v188
	v_exp_f32_e32 v189, v189
	v_exp_f32_e32 v190, v190
	v_exp_f32_e32 v191, v191
	v_pk_add_f32 v[184:185], v[184:185], v[222:223]
	v_pk_add_f32 v[186:187], v[186:187], v[222:223]
	v_pk_add_f32 v[188:189], v[188:189], v[222:223]
	v_pk_add_f32 v[190:191], v[190:191], v[222:223]
	v_rcp_f32_e32 v184, v184
	v_rcp_f32_e32 v185, v185
	v_rcp_f32_e32 v186, v186
	v_rcp_f32_e32 v187, v187
	v_rcp_f32_e32 v188, v188
	v_rcp_f32_e32 v189, v189
	v_rcp_f32_e32 v190, v190
	v_rcp_f32_e32 v191, v191
	v_pk_mul_f32 v[184:185], v[176:177], v[184:185]
	v_pk_mul_f32 v[186:187], v[178:179], v[186:187]
	v_pk_mul_f32 v[188:189], v[180:181], v[188:189]
	v_pk_mul_f32 v[190:191], v[182:183], v[190:191]
	v_cvt_pk_bf16_f32 v192, v184, v185
	v_cvt_pk_bf16_f32 v193, v186, v187
	v_cvt_pk_bf16_f32 v194, v188, v189
	v_cvt_pk_bf16_f32 v195, v190, v191
	global_store_dwordx4 v108, v[192:195], s[52:53] sc1
	v_add_u32_e32 v108, 0x2000, v108
	s_add_i32 s56, s56, 1
	s_waitcnt vmcnt(11)
	s_cmp_lt_u32 s56, 0x4000
	s_cselect_b32 s57, 0x7ff, 7
	s_and_b32 s57, s56, s57
	s_cmp_eq_u32 s57, 0
	s_cbranch_scc0 .Lcv_a3_x
	s_cmp_lt_u32 s56, 0x4000
	s_cbranch_scc0 .Lcv_a3_s
	v_mov_b32_e32 v144, 0
	v_mov_b32_e32 v145, 0
	v_mov_b32_e32 v146, 0
	v_mov_b32_e32 v147, 0
	v_mov_b32_e32 v148, 0
	v_mov_b32_e32 v149, 0
	v_mov_b32_e32 v150, 0
	v_mov_b32_e32 v151, 0
	v_mov_b32_e32 v152, 0
	v_mov_b32_e32 v153, 0
	v_mov_b32_e32 v154, 0
	v_mov_b32_e32 v155, 0
	v_mov_b32_e32 v156, 0
	v_mov_b32_e32 v157, 0
	v_mov_b32_e32 v158, 0
	v_mov_b32_e32 v159, 0
	v_mov_b32_e32 v160, 0
	v_mov_b32_e32 v161, 0
	v_mov_b32_e32 v162, 0
	v_mov_b32_e32 v163, 0
	v_mov_b32_e32 v164, 0
	v_mov_b32_e32 v165, 0
	v_mov_b32_e32 v166, 0
	v_mov_b32_e32 v167, 0
	s_branch .Lcv_a3_x

; __device__ __forceinline__ float silu(float x) { return x * __builtin_amdgcn_rcpf(1.0f + __expf(-x)); }
; __device__ void phase_conv(const Params& p, unsigned char* smem, const int rep) {
;     ...
;     for (int r4 = 0; r4 < rows_per; r4 += 4) {
; #pragma unroll
;       for (int q = 0; q < 4; ++q) {
;         nxt[q] = cur[q];
;         if (r4 + 4 + q < rows_per) nxt[q] = *(const u32x4*)(proj + (size_t)(rbeg + r4 + 4 + q) * PROJ_LD + 2048 + ch0);
;       }
;     ...
;         float xc[8], o[8];
;         unpack8(cur[q4], xc);
; #pragma unroll
;         for (int q = 0; q < 8; ++q) {
;           const float a = bs[q] + hm3[q] * wgt[0][q] + hm2[q] * wgt[1][q] + hm1[q] * wgt[2][q] + xc[q] * wgt[3][q];
;           o[q] = silu(a);
;           hm3[q] = hm2[q]; hm2[q] = hm1[q]; hm1[q] = xc[q];
;         }
;         u32x4 ov;
;         ov.x = pack2(o[0], o[1]); ov.y = pack2(o[2], o[3]); ov.z = pack2(o[4], o[5]); ov.w = pack2(o[6], o[7]);
;         *(u32x4*)(xbcc + (size_t)row * 4096 + ch0) = ov;
.Lcv_a3_x:
	v_lshlrev_b32_e32 v168, 16, v124
	v_and_b32_e32 v169, 0xffff0000, v124
	v_lshlrev_b32_e32 v170, 16, v125
	v_and_b32_e32 v171, 0xffff0000, v125
	v_lshlrev_b32_e32 v172, 16, v126
	v_and_b32_e32 v173, 0xffff0000, v126
	v_lshlrev_b32_e32 v174, 16, v127
	v_and_b32_e32 v175, 0xffff0000, v127
	v_pk_fma_f32 v[176:177], v[32:33], v[144:145], v[36:37]
	v_pk_fma_f32 v[178:179], v[34:35], v[146:147], v[38:39]
	v_pk_fma_f32 v[180:181], v[24:25], v[148:149], v[28:29]
	v_pk_fma_f32 v[182:183], v[26:27], v[150:151], v[30:31]
	v_pk_fma_f32 v[176:177], v[16:17], v[152:153], v[176:177]
	v_pk_fma_f32 v[178:179], v[18:19], v[154:155], v[178:179]
	v_pk_fma_f32 v[180:181], v[0:1], v[156:157], v[180:181]
	v_pk_fma_f32 v[182:183], v[2:3], v[158:159], v[182:183]
	v_pk_fma_f32 v[176:177], v[8:9], v[160:161], v[176:177]
	v_pk_fma_f32 v[178:179], v[10:11], v[162:163], v[178:179]
	v_pk_fma_f32 v[180:181], v[4:5], v[164:165], v[180:181]
	v_pk_fma_f32 v[182:183], v[6:7], v[166:167], v[182:183]
	v_pk_fma_f32 v[176:177], v[12:13], v[168:169], v[176:177]
	v_pk_fma_f32 v[178:179], v[14:15], v[170:171], v[178:179]
	v_pk_fma_f32 v[180:181], v[20:21], v[172:173], v[180:181]
	v_pk_fma_f32 v[182:183], v[22:23], v[174:175], v[182:183]
	v_pk_mul_f32 v[184:185], v[176:177], v[220:221]
	v_pk_mul_f32 v[186:187], v[178:179], v[220:221]
	v_pk_mul_f32 v[188:189], v[180:181], v[220:221]
	v_pk_mul_f32 v[190:191], v[182:183], v[220:221]
	v_exp_f32_e32 v184, v184
	v_exp_f32_e32 v185, v185
	v_exp_f32_e32 v186, v186
	v_exp_f32_e32 v187, v187
	v_exp_f32_e32 v188, v188
	v_exp_f32_e32 v189, v189
	v_exp_f32_e32 v190, v190
	v_exp_f32_e32 v191, v191
	v_pk_add_f32 v[184:185], v[184:185], v[222:223]
	v_pk_add_f32 v[186:187], v[186:187], v[222:223]
	v_pk_add_f32 v[188:189], v[188:189], v[222:223]
	v_pk_add_f32 v[190:191], v[190:191], v[222:223]
	v_rcp_f32_e32 v184, v184
	v_rcp_f32_e32 v185, v185
	v_rcp_f32_e32 v186, v186
	v_rcp_f32_e32 v187, v187
	v_rcp_f32_e32 v188, v188
	v_rcp_f32_e32 v189, v189
	v_rcp_f32_e32 v190, v190
	v_rcp_f32_e32 v191, v191
	v_pk_mul_f32 v[184:185], v[176:177], v[184:185]
	v_pk_mul_f32 v[186:187], v[178:179], v[186:187]
	v_pk_mul_f32 v[188:189], v[180:181], v[188:189]
	v_pk_mul_f32 v[190:191], v[182:183], v[190:191]
	v_cvt_pk_bf16_f32 v192, v184, v185
	v_cvt_pk_bf16_f32 v193, v186, v187
	v_cvt_pk_bf16_f32 v194, v188, v189
	v_cvt_pk_bf16_f32 v195, v190, v191
	global_store_dwordx4 v108, v[192:195], s[52:53] sc1
	v_add_u32_e32 v108, 0x2000, v108
	s_add_i32 s56, s56, 1
	global_load_dwordx4 v[112:115], v107, s[50:51]
	v_add_u32_e32 v107, 0x3080, v107
	global_load_dwordx4 v[116:119], v107, s[50:51]
	v_add_u32_e32 v107, 0x3080, v107
	global_load_dwordx4 v[120:123], v107, s[50:51]
	v_add_u32_e32 v107, 0x3080, v107
	global_load_dwordx4 v[124:127], v107, s[50:51]
	v_add_u32_e32 v107, 0x3080, v107
	s_waitcnt vmcnt(11)
	s_cmp_lt_u32 s56, 0x4000
	s_cselect_b32 s57, 0x7ff, 7
	s_and_b32 s57, s56, s57
	s_cmp_eq_u32 s57, 0
	s_cbranch_scc0 .Lcv_b0_x
	s_cmp_lt_u32 s56, 0x4000
	s_cbranch_scc0 .Lcv_b0_s
	v_mov_b32_e32 v152, 0
	v_mov_b32_e32 v153, 0
	v_mov_b32_e32 v154, 0
	v_mov_b32_e32 v155, 0
	v_mov_b32_e32 v156, 0
	v_mov_b32_e32 v157, 0
	v_mov_b32_e32 v158, 0
	v_mov_b32_e32 v159, 0
	v_mov_b32_e32 v160, 0
	v_mov_b32_e32 v161, 0
	v_mov_b32_e32 v162, 0
	v_mov_b32_e32 v163, 0
	v_mov_b32_e32 v164, 0
	v_mov_b32_e32 v165, 0
	v_mov_b32_e32 v166, 0
	v_mov_b32_e32 v167, 0
	v_mov_b32_e32 v168, 0
	v_mov_b32_e32 v169, 0
	v_mov_b32_e32 v170, 0
	v_mov_b32_e32 v171, 0
	v_mov_b32_e32 v172, 0
	v_mov_b32_e32 v173, 0
	v_mov_b32_e32 v174, 0
	v_mov_b32_e32 v175, 0
	s_branch .Lcv_b0_x

; __device__ __forceinline__ float silu(float x) { return x * __builtin_amdgcn_rcpf(1.0f + __expf(-x)); }
; __device__ void phase_conv(const Params& p, unsigned char* smem, const int rep) {
;     ...
;         const bool samp = row >= NPROMPT;
;         const int t = samp ? ((row - NPROMPT) & 7) : (row & 2047);
;         const int b = samp ? ((row - NPROMPT) >> 3) : (row >> 11);
;         if (r == 0 || t == 0) {
; #pragma unroll
;           for (int k = 1; k <= 3; ++k) {
;             float hv[8];
;             if (t - k >= 0) {
;               unpack8(*(const u32x4*)(proj + (size_t)(row - k) * PROJ_LD + 2048 + ch0), hv);
;             } else if (samp) {
;               const float* sp = p.state_conv + ((size_t)b * 3 + (t - k + 3)) * 4096 + ch0;
;               const float4 s0 = *(const float4*)sp, s1 = *(const float4*)(sp + 4);
;               hv[0] = s0.x; hv[1] = s0.y; hv[2] = s0.z; hv[3] = s0.w; hv[4] = s1.x; hv[5] = s1.y; hv[6] = s1.z; hv[7] = s1.w;
;             } else {
; #pragma unroll
;               for (int q = 0; q < 8; ++q) hv[q] = 0.f;
;     ...
;         float xc[8], o[8];
;         unpack8(cur[q4], xc);
; #pragma unroll
;         for (int q = 0; q < 8; ++q) {
;           const float a = bs[q] + hm3[q] * wgt[0][q] + hm2[q] * wgt[1][q] + hm1[q] * wgt[2][q] + xc[q] * wgt[3][q];
;           o[q] = silu(a);
;           hm3[q] = hm2[q]; hm2[q] = hm1[q]; hm1[q] = xc[q];
;         }
;         u32x4 ov;
;         ov.x = pack2(o[0], o[1]); ov.y = pack2(o[2], o[3]); ov.z = pack2(o[4], o[5]); ov.w = pack2(o[6], o[7]);
;         *(u32x4*)(xbcc + (size_t)row * 4096 + ch0) = ov;
.Lcv_b0_x:
	v_lshlrev_b32_e32 v144, 16, v128
	v_and_b32_e32 v145, 0xffff0000, v128
	v_lshlrev_b32_e32 v146, 16, v129
	v_and_b32_e32 v147, 0xffff0000, v129
	v_lshlrev_b32_e32 v148, 16, v130
	v_and_b32_e32 v149, 0xffff0000, v130
	v_lshlrev_b32_e32 v150, 16, v131
	v_and_b32_e32 v151, 0xffff0000, v131
	v_pk_fma_f32 v[176:177], v[32:33], v[152:153], v[36:37]
	v_pk_fma_f32 v[178:179], v[34:35], v[154:155], v[38:39]
	v_pk_fma_f32 v[180:181], v[24:25], v[156:157], v[28:29]
	v_pk_fma_f32 v[182:183], v[26:27], v[158:159], v[30:31]
	v_pk_fma_f32 v[176:177], v[16:17], v[160:161], v[176:177]
	v_pk_fma_f32 v[178:179], v[18:19], v[162:163], v[178:179]
	v_pk_fma_f32 v[180:181], v[0:1], v[164:165], v[180:181]
	v_pk_fma_f32 v[182:183], v[2:3], v[166:167], v[182:183]
	v_pk_fma_f32 v[176:177], v[8:9], v[168:169], v[176:177]
	v_pk_fma_f32 v[178:179], v[10:11], v[170:171], v[178:179]
	v_pk_fma_f32 v[180:181], v[4:5], v[172:173], v[180:181]
	v_pk_fma_f32 v[182:183], v[6:7], v[174:175], v[182:183]
	v_pk_fma_f32 v[176:177], v[12:13], v[144:145], v[176:177]
	v_pk_fma_f32 v[178:179], v[14:15], v[146:147], v[178:179]
	v_pk_fma_f32 v[180:181], v[20:21], v[148:149], v[180:181]
	v_pk_fma_f32 v[182:183], v[22:23], v[150:151], v[182:183]
	v_pk_mul_f32 v[184:185], v[176:177], v[220:221]
	v_pk_mul_f32 v[186:187], v[178:179], v[220:221]
	v_pk_mul_f32 v[188:189], v[180:181], v[220:221]
	v_pk_mul_f32 v[190:191], v[182:183], v[220:221]
	v_exp_f32_e32 v184, v184
	v_exp_f32_e32 v185, v185
	v_exp_f32_e32 v186, v186
	v_exp_f32_e32 v187, v187
	v_exp_f32_e32 v188, v188
	v_exp_f32_e32 v189, v189
	v_exp_f32_e32 v190, v190
	v_exp_f32_e32 v191, v191
	v_pk_add_f32 v[184:185], v[184:185], v[222:223]
	v_pk_add_f32 v[186:187], v[186:187], v[222:223]
	v_pk_add_f32 v[188:189], v[188:189], v[222:223]
	v_pk_add_f32 v[190:191], v[190:191], v[222:223]
	v_rcp_f32_e32 v184, v184
	v_rcp_f32_e32 v185, v185
	v_rcp_f32_e32 v186, v186
	v_rcp_f32_e32 v187, v187
	v_rcp_f32_e32 v188, v188
	v_rcp_f32_e32 v189, v189
	v_rcp_f32_e32 v190, v190
	v_rcp_f32_e32 v191, v191
	v_pk_mul_f32 v[184:185], v[176:177], v[184:185]
	v_pk_mul_f32 v[186:187], v[178:179], v[186:187]
	v_pk_mul_f32 v[188:189], v[180:181], v[188:189]
	v_pk_mul_f32 v[190:191], v[182:183], v[190:191]
	v_cvt_pk_bf16_f32 v192, v184, v185
	v_cvt_pk_bf16_f32 v193, v186, v187
	v_cvt_pk_bf16_f32 v194, v188, v189
	v_cvt_pk_bf16_f32 v195, v190, v191
	global_store_dwordx4 v108, v[192:195], s[52:53] sc1
	v_add_u32_e32 v108, 0x2000, v108
	s_add_i32 s56, s56, 1
	s_waitcnt vmcnt(11)
	s_cmp_lt_u32 s56, 0x4000
	s_cselect_b32 s57, 0x7ff, 7
	s_and_b32 s57, s56, s57
	s_cmp_eq_u32 s57, 0
	s_cbranch_scc0 .Lcv_b1_x
	s_cmp_lt_u32 s56, 0x4000
	s_cbranch_scc0 .Lcv_b1_s
	v_mov_b32_e32 v160, 0
	v_mov_b32_e32 v161, 0
	v_mov_b32_e32 v162, 0
	v_mov_b32_e32 v163, 0
	v_mov_b32_e32 v164, 0
	v_mov_b32_e32 v165, 0
	v_mov_b32_e32 v166, 0
	v_mov_b32_e32 v167, 0
	v_mov_b32_e32 v168, 0
	v_mov_b32_e32 v169, 0
	v_mov_b32_e32 v170, 0
	v_mov_b32_e32 v171, 0
	v_mov_b32_e32 v172, 0
	v_mov_b32_e32 v173, 0
	v_mov_b32_e32 v174, 0
	v_mov_b32_e32 v175, 0
	v_mov_b32_e32 v144, 0
	v_mov_b32_e32 v145, 0
	v_mov_b32_e32 v146, 0
	v_mov_b32_e32 v147, 0
	v_mov_b32_e32 v148, 0
	v_mov_b32_e32 v149, 0
	v_mov_b32_e32 v150, 0
	v_mov_b32_e32 v151, 0
	s_branch .Lcv_b1_x

; __device__ __forceinline__ float silu(float x) { return x * __builtin_amdgcn_rcpf(1.0f + __expf(-x)); }
; __device__ void phase_conv(const Params& p, unsigned char* smem, const int rep) {
;     ...
;         const bool samp = row >= NPROMPT;
;         const int t = samp ? ((row - NPROMPT) & 7) : (row & 2047);
;         const int b = samp ? ((row - NPROMPT) >> 3) : (row >> 11);
;         if (r == 0 || t == 0) {
; #pragma unroll
;           for (int k = 1; k <= 3; ++k) {
;             float hv[8];
;             if (t - k >= 0) {
;               unpack8(*(const u32x4*)(proj + (size_t)(row - k) * PROJ_LD + 2048 + ch0), hv);
;             } else if (samp) {
;               const float* sp = p.state_conv + ((size_t)b * 3 + (t - k + 3)) * 4096 + ch0;
;               const float4 s0 = *(const float4*)sp, s1 = *(const float4*)(sp + 4);
;               hv[0] = s0.x; hv[1] = s0.y; hv[2] = s0.z; hv[3] = s0.w; hv[4] = s1.x; hv[5] = s1.y; hv[6] = s1.z; hv[7] = s1.w;
;             } else {
; #pragma unroll
;               for (int q = 0; q < 8; ++q) hv[q] = 0.f;
;     ...
;         float xc[8], o[8];
;         unpack8(cur[q4], xc);
; #pragma unroll
;         for (int q = 0; q < 8; ++q) {
;           const float a = bs[q] + hm3[q] * wgt[0][q] + hm2[q] * wgt[1][q] + hm1[q] * wgt[2][q] + xc[q] * wgt[3][q];
;           o[q] = silu(a);
;           hm3[q] = hm2[q]; hm2[q] = hm1[q]; hm1[q] = xc[q];
;         }
;         u32x4 ov;
;         ov.x = pack2(o[0], o[1]); ov.y = pack2(o[2], o[3]); ov.z = pack2(o[4], o[5]); ov.w = pack2(o[6], o[7]);
;         *(u32x4*)(xbcc + (size_t)row * 4096 + ch0) = ov;
.Lcv_b1_x:
	v_lshlrev_b32_e32 v152, 16, v132
	v_and_b32_e32 v153, 0xffff0000, v132
	v_lshlrev_b32_e32 v154, 16, v133
	v_and_b32_e32 v155, 0xffff0000, v133
	v_lshlrev_b32_e32 v156, 16, v134
	v_and_b32_e32 v157, 0xffff0000, v134
	v_lshlrev_b32_e32 v158, 16, v135
	v_and_b32_e32 v159, 0xffff0000, v135
	v_pk_fma_f32 v[176:177], v[32:33], v[160:161], v[36:37]
	v_pk_fma_f32 v[178:179], v[34:35], v[162:163], v[38:39]
	v_pk_fma_f32 v[180:181], v[24:25], v[164:165], v[28:29]
	v_pk_fma_f32 v[182:183], v[26:27], v[166:167], v[30:31]
	v_pk_fma_f32 v[176:177], v[16:17], v[168:169], v[176:177]
	v_pk_fma_f32 v[178:179], v[18:19], v[170:171], v[178:179]
	v_pk_fma_f32 v[180:181], v[0:1], v[172:173], v[180:181]
	v_pk_fma_f32 v[182:183], v[2:3], v[174:175], v[182:183]
	v_pk_fma_f32 v[176:177], v[8:9], v[144:145], v[176:177]
	v_pk_fma_f32 v[178:179], v[10:11], v[146:147], v[178:179]
	v_pk_fma_f32 v[180:181], v[4:5], v[148:149], v[180:181]
	v_pk_fma_f32 v[182:183], v[6:7], v[150:151], v[182:183]
	v_pk_fma_f32 v[176:177], v[12:13], v[152:153], v[176:177]
	v_pk_fma_f32 v[178:179], v[14:15], v[154:155], v[178:179]
	v_pk_fma_f32 v[180:181], v[20:21], v[156:157], v[180:181]
	v_pk_fma_f32 v[182:183], v[22:23], v[158:159], v[182:183]
	v_pk_mul_f32 v[184:185], v[176:177], v[220:221]
	v_pk_mul_f32 v[186:187], v[178:179], v[220:221]
	v_pk_mul_f32 v[188:189], v[180:181], v[220:221]
	v_pk_mul_f32 v[190:191], v[182:183], v[220:221]
	v_exp_f32_e32 v184, v184
	v_exp_f32_e32 v185, v185
	v_exp_f32_e32 v186, v186
	v_exp_f32_e32 v187, v187
	v_exp_f32_e32 v188, v188
	v_exp_f32_e32 v189, v189
	v_exp_f32_e32 v190, v190
	v_exp_f32_e32 v191, v191
	v_pk_add_f32 v[184:185], v[184:185], v[222:223]
	v_pk_add_f32 v[186:187], v[186:187], v[222:223]
	v_pk_add_f32 v[188:189], v[188:189], v[222:223]
	v_pk_add_f32 v[190:191], v[190:191], v[222:223]
	v_rcp_f32_e32 v184, v184
	v_rcp_f32_e32 v185, v185
	v_rcp_f32_e32 v186, v186
	v_rcp_f32_e32 v187, v187
	v_rcp_f32_e32 v188, v188
	v_rcp_f32_e32 v189, v189
	v_rcp_f32_e32 v190, v190
	v_rcp_f32_e32 v191, v191
	v_pk_mul_f32 v[184:185], v[176:177], v[184:185]
	v_pk_mul_f32 v[186:187], v[178:179], v[186:187]
	v_pk_mul_f32 v[188:189], v[180:181], v[188:189]
	v_pk_mul_f32 v[190:191], v[182:183], v[190:191]
	v_cvt_pk_bf16_f32 v192, v184, v185
	v_cvt_pk_bf16_f32 v193, v186, v187
	v_cvt_pk_bf16_f32 v194, v188, v189
	v_cvt_pk_bf16_f32 v195, v190, v191
	global_store_dwordx4 v108, v[192:195], s[52:53] sc1
	v_add_u32_e32 v108, 0x2000, v108
	s_add_i32 s56, s56, 1
	s_waitcnt vmcnt(11)
	s_cmp_lt_u32 s56, 0x4000
	s_cselect_b32 s57, 0x7ff, 7
	s_and_b32 s57, s56, s57
	s_cmp_eq_u32 s57, 0
	s_cbranch_scc0 .Lcv_b2_x
	s_cmp_lt_u32 s56, 0x4000
	s_cbranch_scc0 .Lcv_b2_s
	v_mov_b32_e32 v168, 0
	v_mov_b32_e32 v169, 0
	v_mov_b32_e32 v170, 0
	v_mov_b32_e32 v171, 0
	v_mov_b32_e32 v172, 0
	v_mov_b32_e32 v173, 0
	v_mov_b32_e32 v174, 0
	v_mov_b32_e32 v175, 0
	v_mov_b32_e32 v144, 0
	v_mov_b32_e32 v145, 0
	v_mov_b32_e32 v146, 0
	v_mov_b32_e32 v147, 0
	v_mov_b32_e32 v148, 0
	v_mov_b32_e32 v149, 0
	v_mov_b32_e32 v150, 0
	v_mov_b32_e32 v151, 0
	v_mov_b32_e32 v152, 0
	v_mov_b32_e32 v153, 0
	v_mov_b32_e32 v154, 0
	v_mov_b32_e32 v155, 0
	v_mov_b32_e32 v156, 0
	v_mov_b32_e32 v157, 0
	v_mov_b32_e32 v158, 0
	v_mov_b32_e32 v159, 0
	s_branch .Lcv_b2_x

; __device__ __forceinline__ float silu(float x) { return x * __builtin_amdgcn_rcpf(1.0f + __expf(-x)); }
; __device__ void phase_conv(const Params& p, unsigned char* smem, const int rep) {
;     ...
;         const bool samp = row >= NPROMPT;
;         const int t = samp ? ((row - NPROMPT) & 7) : (row & 2047);
;         const int b = samp ? ((row - NPROMPT) >> 3) : (row >> 11);
;         if (r == 0 || t == 0) {
; #pragma unroll
;           for (int k = 1; k <= 3; ++k) {
;             float hv[8];
;             if (t - k >= 0) {
;               unpack8(*(const u32x4*)(proj + (size_t)(row - k) * PROJ_LD + 2048 + ch0), hv);
;             } else if (samp) {
;               const float* sp = p.state_conv + ((size_t)b * 3 + (t - k + 3)) * 4096 + ch0;
;               const float4 s0 = *(const float4*)sp, s1 = *(const float4*)(sp + 4);
;               hv[0] = s0.x; hv[1] = s0.y; hv[2] = s0.z; hv[3] = s0.w; hv[4] = s1.x; hv[5] = s1.y; hv[6] = s1.z; hv[7] = s1.w;
;             } else {
; #pragma unroll
;               for (int q = 0; q < 8; ++q) hv[q] = 0.f;
;     ...
;         float xc[8], o[8];
;         unpack8(cur[q4], xc);
; #pragma unroll
;         for (int q = 0; q < 8; ++q) {
;           const float a = bs[q] + hm3[q] * wgt[0][q] + hm2[q] * wgt[1][q] + hm1[q] * wgt[2][q] + xc[q] * wgt[3][q];
;           o[q] = silu(a);
;           hm3[q] = hm2[q]; hm2[q] = hm1[q]; hm1[q] = xc[q];
;         }
;         u32x4 ov;
;         ov.x = pack2(o[0], o[1]); ov.y = pack2(o[2], o[3]); ov.z = pack2(o[4], o[5]); ov.w = pack2(o[6], o[7]);
;         *(u32x4*)(xbcc + (size_t)row * 4096 + ch0) = ov;
.Lcv_b2_x:
	v_lshlrev_b32_e32 v160, 16, v136
	v_and_b32_e32 v161, 0xffff0000, v136
	v_lshlrev_b32_e32 v162, 16, v137
	v_and_b32_e32 v163, 0xffff0000, v137
	v_lshlrev_b32_e32 v164, 16, v138
	v_and_b32_e32 v165, 0xffff0000, v138
	v_lshlrev_b32_e32 v166, 16, v139
	v_and_b32_e32 v167, 0xffff0000, v139
	v_pk_fma_f32 v[176:177], v[32:33], v[168:169], v[36:37]
	v_pk_fma_f32 v[178:179], v[34:35], v[170:171], v[38:39]
	v_pk_fma_f32 v[180:181], v[24:25], v[172:173], v[28:29]
	v_pk_fma_f32 v[182:183], v[26:27], v[174:175], v[30:31]
	v_pk_fma_f32 v[176:177], v[16:17], v[144:145], v[176:177]
	v_pk_fma_f32 v[178:179], v[18:19], v[146:147], v[178:179]
	v_pk_fma_f32 v[180:181], v[0:1], v[148:149], v[180:181]
	v_pk_fma_f32 v[182:183], v[2:3], v[150:151], v[182:183]
	v_pk_fma_f32 v[176:177], v[8:9], v[152:153], v[176:177]
	v_pk_fma_f32 v[178:179], v[10:11], v[154:155], v[178:179]
	v_pk_fma_f32 v[180:181], v[4:5], v[156:157], v[180:181]
	v_pk_fma_f32 v[182:183], v[6:7], v[158:159], v[182:183]
	v_pk_fma_f32 v[176:177], v[12:13], v[160:161], v[176:177]
	v_pk_fma_f32 v[178:179], v[14:15], v[162:163], v[178:179]
	v_pk_fma_f32 v[180:181], v[20:21], v[164:165], v[180:181]
	v_pk_fma_f32 v[182:183], v[22:23], v[166:167], v[182:183]
	v_pk_mul_f32 v[184:185], v[176:177], v[220:221]
	v_pk_mul_f32 v[186:187], v[178:179], v[220:221]
	v_pk_mul_f32 v[188:189], v[180:181], v[220:221]
	v_pk_mul_f32 v[190:191], v[182:183], v[220:221]
	v_exp_f32_e32 v184, v184
	v_exp_f32_e32 v185, v185
	v_exp_f32_e32 v186, v186
	v_exp_f32_e32 v187, v187
	v_exp_f32_e32 v188, v188
	v_exp_f32_e32 v189, v189
	v_exp_f32_e32 v190, v190
	v_exp_f32_e32 v191, v191
	v_pk_add_f32 v[184:185], v[184:185], v[222:223]
	v_pk_add_f32 v[186:187], v[186:187], v[222:223]
	v_pk_add_f32 v[188:189], v[188:189], v[222:223]
	v_pk_add_f32 v[190:191], v[190:191], v[222:223]
	v_rcp_f32_e32 v184, v184
	v_rcp_f32_e32 v185, v185
	v_rcp_f32_e32 v186, v186
	v_rcp_f32_e32 v187, v187
	v_rcp_f32_e32 v188, v188
	v_rcp_f32_e32 v189, v189
	v_rcp_f32_e32 v190, v190
	v_rcp_f32_e32 v191, v191
	v_pk_mul_f32 v[184:185], v[176:177], v[184:185]
	v_pk_mul_f32 v[186:187], v[178:179], v[186:187]
	v_pk_mul_f32 v[188:189], v[180:181], v[188:189]
	v_pk_mul_f32 v[190:191], v[182:183], v[190:191]
	v_cvt_pk_bf16_f32 v192, v184, v185
	v_cvt_pk_bf16_f32 v193, v186, v187
	v_cvt_pk_bf16_f32 v194, v188, v189
	v_cvt_pk_bf16_f32 v195, v190, v191
	global_store_dwordx4 v108, v[192:195], s[52:53] sc1
	v_add_u32_e32 v108, 0x2000, v108
	s_add_i32 s56, s56, 1
	s_waitcnt vmcnt(11)
	s_cmp_lt_u32 s56, 0x4000
	s_cselect_b32 s57, 0x7ff, 7
	s_and_b32 s57, s56, s57
	s_cmp_eq_u32 s57, 0
	s_cbranch_scc0 .Lcv_b3_x
	s_cmp_lt_u32 s56, 0x4000
	s_cbranch_scc0 .Lcv_b3_s
	v_mov_b32_e32 v144, 0
	v_mov_b32_e32 v145, 0
	v_mov_b32_e32 v146, 0
	v_mov_b32_e32 v147, 0
	v_mov_b32_e32 v148, 0
	v_mov_b32_e32 v149, 0
	v_mov_b32_e32 v150, 0
	v_mov_b32_e32 v151, 0
	v_mov_b32_e32 v152, 0
	v_mov_b32_e32 v153, 0
	v_mov_b32_e32 v154, 0
	v_mov_b32_e32 v155, 0
	v_mov_b32_e32 v156, 0
	v_mov_b32_e32 v157, 0
	v_mov_b32_e32 v158, 0
	v_mov_b32_e32 v159, 0
	v_mov_b32_e32 v160, 0
	v_mov_b32_e32 v161, 0
	v_mov_b32_e32 v162, 0
	v_mov_b32_e32 v163, 0
	v_mov_b32_e32 v164, 0
	v_mov_b32_e32 v165, 0
	v_mov_b32_e32 v166, 0
	v_mov_b32_e32 v167, 0
	s_branch .Lcv_b3_x

; __device__ __forceinline__ float silu(float x) { return x * __builtin_amdgcn_rcpf(1.0f + __expf(-x)); }
; __device__ void phase_conv(const Params& p, unsigned char* smem, const int rep) {
;     ...
;         float xc[8], o[8];
;         unpack8(cur[q4], xc);
; #pragma unroll
;         for (int q = 0; q < 8; ++q) {
;           const float a = bs[q] + hm3[q] * wgt[0][q] + hm2[q] * wgt[1][q] + hm1[q] * wgt[2][q] + xc[q] * wgt[3][q];
;           o[q] = silu(a);
;           hm3[q] = hm2[q]; hm2[q] = hm1[q]; hm1[q] = xc[q];
;         }
;         u32x4 ov;
;         ov.x = pack2(o[0], o[1]); ov.y = pack2(o[2], o[3]); ov.z = pack2(o[4], o[5]); ov.w = pack2(o[6], o[7]);
;         *(u32x4*)(xbcc + (size_t)row * 4096 + ch0) = ov;
;       }
; #pragma unroll
;       for (int q = 0; q < 4; ++q) cur[q] = nxt[q];
;     }
.Lcv_b3_x:
	v_lshlrev_b32_e32 v168, 16, v140
	v_and_b32_e32 v169, 0xffff0000, v140
	v_lshlrev_b32_e32 v170, 16, v141
	v_and_b32_e32 v171, 0xffff0000, v141
	v_lshlrev_b32_e32 v172, 16, v142
	v_and_b32_e32 v173, 0xffff0000, v142
	v_lshlrev_b32_e32 v174, 16, v143
	v_and_b32_e32 v175, 0xffff0000, v143
	v_pk_fma_f32 v[176:177], v[32:33], v[144:145], v[36:37]
	v_pk_fma_f32 v[178:179], v[34:35], v[146:147], v[38:39]
	v_pk_fma_f32 v[180:181], v[24:25], v[148:149], v[28:29]
	v_pk_fma_f32 v[182:183], v[26:27], v[150:151], v[30:31]
	v_pk_fma_f32 v[176:177], v[16:17], v[152:153], v[176:177]
	v_pk_fma_f32 v[178:179], v[18:19], v[154:155], v[178:179]
	v_pk_fma_f32 v[180:181], v[0:1], v[156:157], v[180:181]
	v_pk_fma_f32 v[182:183], v[2:3], v[158:159], v[182:183]
	v_pk_fma_f32 v[176:177], v[8:9], v[160:161], v[176:177]
	v_pk_fma_f32 v[178:179], v[10:11], v[162:163], v[178:179]
	v_pk_fma_f32 v[180:181], v[4:5], v[164:165], v[180:181]
	v_pk_fma_f32 v[182:183], v[6:7], v[166:167], v[182:183]
	v_pk_fma_f32 v[176:177], v[12:13], v[168:169], v[176:177]
	v_pk_fma_f32 v[178:179], v[14:15], v[170:171], v[178:179]
	v_pk_fma_f32 v[180:181], v[20:21], v[172:173], v[180:181]
	v_pk_fma_f32 v[182:183], v[22:23], v[174:175], v[182:183]
	v_pk_mul_f32 v[184:185], v[176:177], v[220:221]
	v_pk_mul_f32 v[186:187], v[178:179], v[220:221]
	v_pk_mul_f32 v[188:189], v[180:181], v[220:221]
	v_pk_mul_f32 v[190:191], v[182:183], v[220:221]
	v_exp_f32_e32 v184, v184
	v_exp_f32_e32 v185, v185
	v_exp_f32_e32 v186, v186
	v_exp_f32_e32 v187, v187
	v_exp_f32_e32 v188, v188
	v_exp_f32_e32 v189, v189
	v_exp_f32_e32 v190, v190
	v_exp_f32_e32 v191, v191
	v_pk_add_f32 v[184:185], v[184:185], v[222:223]
	v_pk_add_f32 v[186:187], v[186:187], v[222:223]
	v_pk_add_f32 v[188:189], v[188:189], v[222:223]
	v_pk_add_f32 v[190:191], v[190:191], v[222:223]
	v_rcp_f32_e32 v184, v184
	v_rcp_f32_e32 v185, v185
	v_rcp_f32_e32 v186, v186
	v_rcp_f32_e32 v187, v187
	v_rcp_f32_e32 v188, v188
	v_rcp_f32_e32 v189, v189
	v_rcp_f32_e32 v190, v190
	v_rcp_f32_e32 v191, v191
	v_pk_mul_f32 v[184:185], v[176:177], v[184:185]
	v_pk_mul_f32 v[186:187], v[178:179], v[186:187]
	v_pk_mul_f32 v[188:189], v[180:181], v[188:189]
	v_pk_mul_f32 v[190:191], v[182:183], v[190:191]
	v_cvt_pk_bf16_f32 v192, v184, v185
	v_cvt_pk_bf16_f32 v193, v186, v187
	v_cvt_pk_bf16_f32 v194, v188, v189
	v_cvt_pk_bf16_f32 v195, v190, v191
	global_store_dwordx4 v108, v[192:195], s[52:53] sc1
	v_add_u32_e32 v108, 0x2000, v108
	s_add_i32 s56, s56, 1
	s_add_i32 s60, s60, 1
	s_cmp_lt_u32 s60, 8
	s_cbranch_scc1 .Lcv_loop
	s_waitcnt vmcnt(7)
	s_cmp_lt_u32 s56, 0x4000
	s_cselect_b32 s57, 0x7ff, 7
	s_and_b32 s57, s56, s57
	s_cmp_eq_u32 s57, 0
	s_cbranch_scc0 .Lcv_c0_x
	s_cmp_lt_u32 s56, 0x4000
	s_cbranch_scc0 .Lcv_c0_s
	v_mov_b32_e32 v152, 0
	v_mov_b32_e32 v153, 0
	v_mov_b32_e32 v154, 0
	v_mov_b32_e32 v155, 0
	v_mov_b32_e32 v156, 0
	v_mov_b32_e32 v157, 0
	v_mov_b32_e32 v158, 0
	v_mov_b32_e32 v159, 0
	v_mov_b32_e32 v160, 0
	v_mov_b32_e32 v161, 0
	v_mov_b32_e32 v162, 0
	v_mov_b32_e32 v163, 0
	v_mov_b32_e32 v164, 0
	v_mov_b32_e32 v165, 0
	v_mov_b32_e32 v166, 0
	v_mov_b32_e32 v167, 0
	v_mov_b32_e32 v168, 0
	v_mov_b32_e32 v169, 0
	v_mov_b32_e32 v170, 0
	v_mov_b32_e32 v171, 0
	v_mov_b32_e32 v172, 0
	v_mov_b32_e32 v173, 0
	v_mov_b32_e32 v174, 0
	v_mov_b32_e32 v175, 0
	s_branch .Lcv_c0_x

; __device__ __forceinline__ float silu(float x) { return x * __builtin_amdgcn_rcpf(1.0f + __expf(-x)); }
; __device__ void phase_conv(const Params& p, unsigned char* smem, const int rep) {
;     ...
;         const bool samp = row >= NPROMPT;
;         const int t = samp ? ((row - NPROMPT) & 7) : (row & 2047);
;         const int b = samp ? ((row - NPROMPT) >> 3) : (row >> 11);
;         if (r == 0 || t == 0) {
; #pragma unroll
;           for (int k = 1; k <= 3; ++k) {
;             float hv[8];
;             if (t - k >= 0) {
;               unpack8(*(const u32x4*)(proj + (size_t)(row - k) * PROJ_LD + 2048 + ch0), hv);
;             } else if (samp) {
;               const float* sp = p.state_conv + ((size_t)b * 3 + (t - k + 3)) * 4096 + ch0;
;               const float4 s0 = *(const float4*)sp, s1 = *(const float4*)(sp + 4);
;               hv[0] = s0.x; hv[1] = s0.y; hv[2] = s0.z; hv[3] = s0.w; hv[4] = s1.x; hv[5] = s1.y; hv[6] = s1.z; hv[7] = s1.w;
;             } else {
; #pragma unroll
;               for (int q = 0; q < 8; ++q) hv[q] = 0.f;
;     ...
;         float xc[8], o[8];
;         unpack8(cur[q4], xc);
; #pragma unroll
;         for (int q = 0; q < 8; ++q) {
;           const float a = bs[q] + hm3[q] * wgt[0][q] + hm2[q] * wgt[1][q] + hm1[q] * wgt[2][q] + xc[q] * wgt[3][q];
;           o[q] = silu(a);
;           hm3[q] = hm2[q]; hm2[q] = hm1[q]; hm1[q] = xc[q];
;         }
;         u32x4 ov;
;         ov.x = pack2(o[0], o[1]); ov.y = pack2(o[2], o[3]); ov.z = pack2(o[4], o[5]); ov.w = pack2(o[6], o[7]);
;         *(u32x4*)(xbcc + (size_t)row * 4096 + ch0) = ov;
.Lcv_c0_x:
	v_lshlrev_b32_e32 v144, 16, v112
	v_and_b32_e32 v145, 0xffff0000, v112
	v_lshlrev_b32_e32 v146, 16, v113
	v_and_b32_e32 v147, 0xffff0000, v113
	v_lshlrev_b32_e32 v148, 16, v114
	v_and_b32_e32 v149, 0xffff0000, v114
	v_lshlrev_b32_e32 v150, 16, v115
	v_and_b32_e32 v151, 0xffff0000, v115
	v_pk_fma_f32 v[176:177], v[32:33], v[152:153], v[36:37]
	v_pk_fma_f32 v[178:179], v[34:35], v[154:155], v[38:39]
	v_pk_fma_f32 v[180:181], v[24:25], v[156:157], v[28:29]
	v_pk_fma_f32 v[182:183], v[26:27], v[158:159], v[30:31]
	v_pk_fma_f32 v[176:177], v[16:17], v[160:161], v[176:177]
	v_pk_fma_f32 v[178:179], v[18:19], v[162:163], v[178:179]
	v_pk_fma_f32 v[180:181], v[0:1], v[164:165], v[180:181]
	v_pk_fma_f32 v[182:183], v[2:3], v[166:167], v[182:183]
	v_pk_fma_f32 v[176:177], v[8:9], v[168:169], v[176:177]
	v_pk_fma_f32 v[178:179], v[10:11], v[170:171], v[178:179]
	v_pk_fma_f32 v[180:181], v[4:5], v[172:173], v[180:181]
	v_pk_fma_f32 v[182:183], v[6:7], v[174:175], v[182:183]
	v_pk_fma_f32 v[176:177], v[12:13], v[144:145], v[176:177]
	v_pk_fma_f32 v[178:179], v[14:15], v[146:147], v[178:179]
	v_pk_fma_f32 v[180:181], v[20:21], v[148:149], v[180:181]
	v_pk_fma_f32 v[182:183], v[22:23], v[150:151], v[182:183]
	v_pk_mul_f32 v[184:185], v[176:177], v[220:221]
	v_pk_mul_f32 v[186:187], v[178:179], v[220:221]
	v_pk_mul_f32 v[188:189], v[180:181], v[220:221]
	v_pk_mul_f32 v[190:191], v[182:183], v[220:221]
	v_exp_f32_e32 v184, v184
	v_exp_f32_e32 v185, v185
	v_exp_f32_e32 v186, v186
	v_exp_f32_e32 v187, v187
	v_exp_f32_e32 v188, v188
	v_exp_f32_e32 v189, v189
	v_exp_f32_e32 v190, v190
	v_exp_f32_e32 v191, v191
	v_pk_add_f32 v[184:185], v[184:185], v[222:223]
	v_pk_add_f32 v[186:187], v[186:187], v[222:223]
	v_pk_add_f32 v[188:189], v[188:189], v[222:223]
	v_pk_add_f32 v[190:191], v[190:191], v[222:223]
	v_rcp_f32_e32 v184, v184
	v_rcp_f32_e32 v185, v185
	v_rcp_f32_e32 v186, v186
	v_rcp_f32_e32 v187, v187
	v_rcp_f32_e32 v188, v188
	v_rcp_f32_e32 v189, v189
	v_rcp_f32_e32 v190, v190
	v_rcp_f32_e32 v191, v191
	v_pk_mul_f32 v[184:185], v[176:177], v[184:185]
	v_pk_mul_f32 v[186:187], v[178:179], v[186:187]
	v_pk_mul_f32 v[188:189], v[180:181], v[188:189]
	v_pk_mul_f32 v[190:191], v[182:183], v[190:191]
	v_cvt_pk_bf16_f32 v192, v184, v185
	v_cvt_pk_bf16_f32 v193, v186, v187
	v_cvt_pk_bf16_f32 v194, v188, v189
	v_cvt_pk_bf16_f32 v195, v190, v191
	global_store_dwordx4 v108, v[192:195], s[52:53] sc1
	v_add_u32_e32 v108, 0x2000, v108
	s_add_i32 s56, s56, 1
	s_waitcnt vmcnt(7)
	s_cmp_lt_u32 s56, 0x4000
	s_cselect_b32 s57, 0x7ff, 7
	s_and_b32 s57, s56, s57
	s_cmp_eq_u32 s57, 0
	s_cbranch_scc0 .Lcv_c1_x
	s_cmp_lt_u32 s56, 0x4000
	s_cbranch_scc0 .Lcv_c1_s
	v_mov_b32_e32 v160, 0
	v_mov_b32_e32 v161, 0
	v_mov_b32_e32 v162, 0
	v_mov_b32_e32 v163, 0
	v_mov_b32_e32 v164, 0
	v_mov_b32_e32 v165, 0
	v_mov_b32_e32 v166, 0
	v_mov_b32_e32 v167, 0
	v_mov_b32_e32 v168, 0
	v_mov_b32_e32 v169, 0
	v_mov_b32_e32 v170, 0
	v_mov_b32_e32 v171, 0
	v_mov_b32_e32 v172, 0
	v_mov_b32_e32 v173, 0
	v_mov_b32_e32 v174, 0
	v_mov_b32_e32 v175, 0
	v_mov_b32_e32 v144, 0
	v_mov_b32_e32 v145, 0
	v_mov_b32_e32 v146, 0
	v_mov_b32_e32 v147, 0
	v_mov_b32_e32 v148, 0
	v_mov_b32_e32 v149, 0
	v_mov_b32_e32 v150, 0
	v_mov_b32_e32 v151, 0
	s_branch .Lcv_c1_x

; __device__ __forceinline__ float silu(float x) { return x * __builtin_amdgcn_rcpf(1.0f + __expf(-x)); }
; __device__ void phase_conv(const Params& p, unsigned char* smem, const int rep) {
;     ...
;         const bool samp = row >= NPROMPT;
;         const int t = samp ? ((row - NPROMPT) & 7) : (row & 2047);
;         const int b = samp ? ((row - NPROMPT) >> 3) : (row >> 11);
;         if (r == 0 || t == 0) {
; #pragma unroll
;           for (int k = 1; k <= 3; ++k) {
;             float hv[8];
;             if (t - k >= 0) {
;               unpack8(*(const u32x4*)(proj + (size_t)(row - k) * PROJ_LD + 2048 + ch0), hv);
;             } else if (samp) {
;               const float* sp = p.state_conv + ((size_t)b * 3 + (t - k + 3)) * 4096 + ch0;
;               const float4 s0 = *(const float4*)sp, s1 = *(const float4*)(sp + 4);
;               hv[0] = s0.x; hv[1] = s0.y; hv[2] = s0.z; hv[3] = s0.w; hv[4] = s1.x; hv[5] = s1.y; hv[6] = s1.z; hv[7] = s1.w;
;             } else {
; #pragma unroll
;               for (int q = 0; q < 8; ++q) hv[q] = 0.f;
;     ...
;         float xc[8], o[8];
;         unpack8(cur[q4], xc);
; #pragma unroll
;         for (int q = 0; q < 8; ++q) {
;           const float a = bs[q] + hm3[q] * wgt[0][q] + hm2[q] * wgt[1][q] + hm1[q] * wgt[2][q] + xc[q] * wgt[3][q];
;           o[q] = silu(a);
;           hm3[q] = hm2[q]; hm2[q] = hm1[q]; hm1[q] = xc[q];
;         }
;         u32x4 ov;
;         ov.x = pack2(o[0], o[1]); ov.y = pack2(o[2], o[3]); ov.z = pack2(o[4], o[5]); ov.w = pack2(o[6], o[7]);
;         *(u32x4*)(xbcc + (size_t)row * 4096 + ch0) = ov;
.Lcv_c1_x:
	v_lshlrev_b32_e32 v152, 16, v116
	v_and_b32_e32 v153, 0xffff0000, v116
	v_lshlrev_b32_e32 v154, 16, v117
	v_and_b32_e32 v155, 0xffff0000, v117
	v_lshlrev_b32_e32 v156, 16, v118
	v_and_b32_e32 v157, 0xffff0000, v118
	v_lshlrev_b32_e32 v158, 16, v119
	v_and_b32_e32 v159, 0xffff0000, v119
	v_pk_fma_f32 v[176:177], v[32:33], v[160:161], v[36:37]
	v_pk_fma_f32 v[178:179], v[34:35], v[162:163], v[38:39]
	v_pk_fma_f32 v[180:181], v[24:25], v[164:165], v[28:29]
	v_pk_fma_f32 v[182:183], v[26:27], v[166:167], v[30:31]
	v_pk_fma_f32 v[176:177], v[16:17], v[168:169], v[176:177]
	v_pk_fma_f32 v[178:179], v[18:19], v[170:171], v[178:179]
	v_pk_fma_f32 v[180:181], v[0:1], v[172:173], v[180:181]
	v_pk_fma_f32 v[182:183], v[2:3], v[174:175], v[182:183]
	v_pk_fma_f32 v[176:177], v[8:9], v[144:145], v[176:177]
	v_pk_fma_f32 v[178:179], v[10:11], v[146:147], v[178:179]
	v_pk_fma_f32 v[180:181], v[4:5], v[148:149], v[180:181]
	v_pk_fma_f32 v[182:183], v[6:7], v[150:151], v[182:183]
	v_pk_fma_f32 v[176:177], v[12:13], v[152:153], v[176:177]
	v_pk_fma_f32 v[178:179], v[14:15], v[154:155], v[178:179]
	v_pk_fma_f32 v[180:181], v[20:21], v[156:157], v[180:181]
	v_pk_fma_f32 v[182:183], v[22:23], v[158:159], v[182:183]
	v_pk_mul_f32 v[184:185], v[176:177], v[220:221]
	v_pk_mul_f32 v[186:187], v[178:179], v[220:221]
	v_pk_mul_f32 v[188:189], v[180:181], v[220:221]
	v_pk_mul_f32 v[190:191], v[182:183], v[220:221]
	v_exp_f32_e32 v184, v184
	v_exp_f32_e32 v185, v185
	v_exp_f32_e32 v186, v186
	v_exp_f32_e32 v187, v187
	v_exp_f32_e32 v188, v188
	v_exp_f32_e32 v189, v189
	v_exp_f32_e32 v190, v190
	v_exp_f32_e32 v191, v191
	v_pk_add_f32 v[184:185], v[184:185], v[222:223]
	v_pk_add_f32 v[186:187], v[186:187], v[222:223]
	v_pk_add_f32 v[188:189], v[188:189], v[222:223]
	v_pk_add_f32 v[190:191], v[190:191], v[222:223]
	v_rcp_f32_e32 v184, v184
	v_rcp_f32_e32 v185, v185
	v_rcp_f32_e32 v186, v186
	v_rcp_f32_e32 v187, v187
	v_rcp_f32_e32 v188, v188
	v_rcp_f32_e32 v189, v189
	v_rcp_f32_e32 v190, v190
	v_rcp_f32_e32 v191, v191
	v_pk_mul_f32 v[184:185], v[176:177], v[184:185]
	v_pk_mul_f32 v[186:187], v[178:179], v[186:187]
	v_pk_mul_f32 v[188:189], v[180:181], v[188:189]
	v_pk_mul_f32 v[190:191], v[182:183], v[190:191]
	v_cvt_pk_bf16_f32 v192, v184, v185
	v_cvt_pk_bf16_f32 v193, v186, v187
	v_cvt_pk_bf16_f32 v194, v188, v189
	v_cvt_pk_bf16_f32 v195, v190, v191
	global_store_dwordx4 v108, v[192:195], s[52:53] sc1
	v_add_u32_e32 v108, 0x2000, v108
	s_add_i32 s56, s56, 1
	s_waitcnt vmcnt(7)
	s_cmp_lt_u32 s56, 0x4000
	s_cselect_b32 s57, 0x7ff, 7
	s_and_b32 s57, s56, s57
	s_cmp_eq_u32 s57, 0
	s_cbranch_scc0 .Lcv_c2_x
	s_cmp_lt_u32 s56, 0x4000
	s_cbranch_scc0 .Lcv_c2_s
	v_mov_b32_e32 v168, 0
	v_mov_b32_e32 v169, 0
	v_mov_b32_e32 v170, 0
	v_mov_b32_e32 v171, 0
	v_mov_b32_e32 v172, 0
	v_mov_b32_e32 v173, 0
	v_mov_b32_e32 v174, 0
	v_mov_b32_e32 v175, 0
	v_mov_b32_e32 v144, 0
	v_mov_b32_e32 v145, 0
	v_mov_b32_e32 v146, 0
	v_mov_b32_e32 v147, 0
	v_mov_b32_e32 v148, 0
	v_mov_b32_e32 v149, 0
	v_mov_b32_e32 v150, 0
	v_mov_b32_e32 v151, 0
	v_mov_b32_e32 v152, 0
	v_mov_b32_e32 v153, 0
	v_mov_b32_e32 v154, 0
	v_mov_b32_e32 v155, 0
	v_mov_b32_e32 v156, 0
	v_mov_b32_e32 v157, 0
	v_mov_b32_e32 v158, 0
	v_mov_b32_e32 v159, 0
	s_branch .Lcv_c2_x

; __device__ __forceinline__ float silu(float x) { return x * __builtin_amdgcn_rcpf(1.0f + __expf(-x)); }
; __device__ void phase_conv(const Params& p, unsigned char* smem, const int rep) {
;     ...
;         const bool samp = row >= NPROMPT;
;         const int t = samp ? ((row - NPROMPT) & 7) : (row & 2047);
;         const int b = samp ? ((row - NPROMPT) >> 3) : (row >> 11);
;         if (r == 0 || t == 0) {
; #pragma unroll
;           for (int k = 1; k <= 3; ++k) {
;             float hv[8];
;             if (t - k >= 0) {
;               unpack8(*(const u32x4*)(proj + (size_t)(row - k) * PROJ_LD + 2048 + ch0), hv);
;             } else if (samp) {
;               const float* sp = p.state_conv + ((size_t)b * 3 + (t - k + 3)) * 4096 + ch0;
;               const float4 s0 = *(const float4*)sp, s1 = *(const float4*)(sp + 4);
;               hv[0] = s0.x; hv[1] = s0.y; hv[2] = s0.z; hv[3] = s0.w; hv[4] = s1.x; hv[5] = s1.y; hv[6] = s1.z; hv[7] = s1.w;
;             } else {
; #pragma unroll
;               for (int q = 0; q < 8; ++q) hv[q] = 0.f;
;     ...
;         float xc[8], o[8];
;         unpack8(cur[q4], xc);
; #pragma unroll
;         for (int q = 0; q < 8; ++q) {
;           const float a = bs[q] + hm3[q] * wgt[0][q] + hm2[q] * wgt[1][q] + hm1[q] * wgt[2][q] + xc[q] * wgt[3][q];
;           o[q] = silu(a);
;           hm3[q] = hm2[q]; hm2[q] = hm1[q]; hm1[q] = xc[q];
;         }
;         u32x4 ov;
;         ov.x = pack2(o[0], o[1]); ov.y = pack2(o[2], o[3]); ov.z = pack2(o[4], o[5]); ov.w = pack2(o[6], o[7]);
;         *(u32x4*)(xbcc + (size_t)row * 4096 + ch0) = ov;
.Lcv_c2_x:
	v_lshlrev_b32_e32 v160, 16, v120
	v_and_b32_e32 v161, 0xffff0000, v120
	v_lshlrev_b32_e32 v162, 16, v121
	v_and_b32_e32 v163, 0xffff0000, v121
	v_lshlrev_b32_e32 v164, 16, v122
	v_and_b32_e32 v165, 0xffff0000, v122
	v_lshlrev_b32_e32 v166, 16, v123
	v_and_b32_e32 v167, 0xffff0000, v123
	v_pk_fma_f32 v[176:177], v[32:33], v[168:169], v[36:37]
	v_pk_fma_f32 v[178:179], v[34:35], v[170:171], v[38:39]
	v_pk_fma_f32 v[180:181], v[24:25], v[172:173], v[28:29]
	v_pk_fma_f32 v[182:183], v[26:27], v[174:175], v[30:31]
	v_pk_fma_f32 v[176:177], v[16:17], v[144:145], v[176:177]
	v_pk_fma_f32 v[178:179], v[18:19], v[146:147], v[178:179]
	v_pk_fma_f32 v[180:181], v[0:1], v[148:149], v[180:181]
	v_pk_fma_f32 v[182:183], v[2:3], v[150:151], v[182:183]
	v_pk_fma_f32 v[176:177], v[8:9], v[152:153], v[176:177]
	v_pk_fma_f32 v[178:179], v[10:11], v[154:155], v[178:179]
	v_pk_fma_f32 v[180:181], v[4:5], v[156:157], v[180:181]
	v_pk_fma_f32 v[182:183], v[6:7], v[158:159], v[182:183]
	v_pk_fma_f32 v[176:177], v[12:13], v[160:161], v[176:177]
	v_pk_fma_f32 v[178:179], v[14:15], v[162:163], v[178:179]
	v_pk_fma_f32 v[180:181], v[20:21], v[164:165], v[180:181]
	v_pk_fma_f32 v[182:183], v[22:23], v[166:167], v[182:183]
	v_pk_mul_f32 v[184:185], v[176:177], v[220:221]
	v_pk_mul_f32 v[186:187], v[178:179], v[220:221]
	v_pk_mul_f32 v[188:189], v[180:181], v[220:221]
	v_pk_mul_f32 v[190:191], v[182:183], v[220:221]
	v_exp_f32_e32 v184, v184
	v_exp_f32_e32 v185, v185
	v_exp_f32_e32 v186, v186
	v_exp_f32_e32 v187, v187
	v_exp_f32_e32 v188, v188
	v_exp_f32_e32 v189, v189
	v_exp_f32_e32 v190, v190
	v_exp_f32_e32 v191, v191
	v_pk_add_f32 v[184:185], v[184:185], v[222:223]
	v_pk_add_f32 v[186:187], v[186:187], v[222:223]
	v_pk_add_f32 v[188:189], v[188:189], v[222:223]
	v_pk_add_f32 v[190:191], v[190:191], v[222:223]
	v_rcp_f32_e32 v184, v184
	v_rcp_f32_e32 v185, v185
	v_rcp_f32_e32 v186, v186
	v_rcp_f32_e32 v187, v187
	v_rcp_f32_e32 v188, v188
	v_rcp_f32_e32 v189, v189
	v_rcp_f32_e32 v190, v190
	v_rcp_f32_e32 v191, v191
	v_pk_mul_f32 v[184:185], v[176:177], v[184:185]
	v_pk_mul_f32 v[186:187], v[178:179], v[186:187]
	v_pk_mul_f32 v[188:189], v[180:181], v[188:189]
	v_pk_mul_f32 v[190:191], v[182:183], v[190:191]
	v_cvt_pk_bf16_f32 v192, v184, v185
	v_cvt_pk_bf16_f32 v193, v186, v187
	v_cvt_pk_bf16_f32 v194, v188, v189
	v_cvt_pk_bf16_f32 v195, v190, v191
	global_store_dwordx4 v108, v[192:195], s[52:53] sc1
	v_add_u32_e32 v108, 0x2000, v108
	s_add_i32 s56, s56, 1
	s_waitcnt vmcnt(7)
	s_cmp_lt_u32 s56, 0x4000
	s_cselect_b32 s57, 0x7ff, 7
	s_and_b32 s57, s56, s57
	s_cmp_eq_u32 s57, 0
	s_cbranch_scc0 .Lcv_c3_x
	s_cmp_lt_u32 s56, 0x4000
	s_cbranch_scc0 .Lcv_c3_s
	v_mov_b32_e32 v144, 0
	v_mov_b32_e32 v145, 0
	v_mov_b32_e32 v146, 0
	v_mov_b32_e32 v147, 0
	v_mov_b32_e32 v148, 0
	v_mov_b32_e32 v149, 0
	v_mov_b32_e32 v150, 0
	v_mov_b32_e32 v151, 0
	v_mov_b32_e32 v152, 0
	v_mov_b32_e32 v153, 0
	v_mov_b32_e32 v154, 0
	v_mov_b32_e32 v155, 0
	v_mov_b32_e32 v156, 0
	v_mov_b32_e32 v157, 0
	v_mov_b32_e32 v158, 0
	v_mov_b32_e32 v159, 0
	v_mov_b32_e32 v160, 0
	v_mov_b32_e32 v161, 0
	v_mov_b32_e32 v162, 0
	v_mov_b32_e32 v163, 0
	v_mov_b32_e32 v164, 0
	v_mov_b32_e32 v165, 0
	v_mov_b32_e32 v166, 0
	v_mov_b32_e32 v167, 0
	s_branch .Lcv_c3_x

; __device__ __forceinline__ float silu(float x) { return x * __builtin_amdgcn_rcpf(1.0f + __expf(-x)); }
; __device__ void phase_conv(const Params& p, unsigned char* smem, const int rep) {
;     ...
;         float xc[8], o[8];
;         unpack8(cur[q4], xc);
; #pragma unroll
;         for (int q = 0; q < 8; ++q) {
;           const float a = bs[q] + hm3[q] * wgt[0][q] + hm2[q] * wgt[1][q] + hm1[q] * wgt[2][q] + xc[q] * wgt[3][q];
;           o[q] = silu(a);
;           hm3[q] = hm2[q]; hm2[q] = hm1[q]; hm1[q] = xc[q];
;         }
;         u32x4 ov;
;         ov.x = pack2(o[0], o[1]); ov.y = pack2(o[2], o[3]); ov.z = pack2(o[4], o[5]); ov.w = pack2(o[6], o[7]);
;         *(u32x4*)(xbcc + (size_t)row * 4096 + ch0) = ov;
.Lcv_c3_x:
	v_lshlrev_b32_e32 v168, 16, v124
	v_and_b32_e32 v169, 0xffff0000, v124
	v_lshlrev_b32_e32 v170, 16, v125
	v_and_b32_e32 v171, 0xffff0000, v125
	v_lshlrev_b32_e32 v172, 16, v126
	v_and_b32_e32 v173, 0xffff0000, v126
	v_lshlrev_b32_e32 v174, 16, v127
	v_and_b32_e32 v175, 0xffff0000, v127
	v_pk_fma_f32 v[176:177], v[32:33], v[144:145], v[36:37]
	v_pk_fma_f32 v[178:179], v[34:35], v[146:147], v[38:39]
	v_pk_fma_f32 v[180:181], v[24:25], v[148:149], v[28:29]
	v_pk_fma_f32 v[182:183], v[26:27], v[150:151], v[30:31]
	v_pk_fma_f32 v[176:177], v[16:17], v[152:153], v[176:177]
	v_pk_fma_f32 v[178:179], v[18:19], v[154:155], v[178:179]
	v_pk_fma_f32 v[180:181], v[0:1], v[156:157], v[180:181]
	v_pk_fma_f32 v[182:183], v[2:3], v[158:159], v[182:183]
	v_pk_fma_f32 v[176:177], v[8:9], v[160:161], v[176:177]
	v_pk_fma_f32 v[178:179], v[10:11], v[162:163], v[178:179]
	v_pk_fma_f32 v[180:181], v[4:5], v[164:165], v[180:181]
	v_pk_fma_f32 v[182:183], v[6:7], v[166:167], v[182:183]
	v_pk_fma_f32 v[176:177], v[12:13], v[168:169], v[176:177]
	v_pk_fma_f32 v[178:179], v[14:15], v[170:171], v[178:179]
	v_pk_fma_f32 v[180:181], v[20:21], v[172:173], v[180:181]
	v_pk_fma_f32 v[182:183], v[22:23], v[174:175], v[182:183]
	v_pk_mul_f32 v[184:185], v[176:177], v[220:221]
	v_pk_mul_f32 v[186:187], v[178:179], v[220:221]
	v_pk_mul_f32 v[188:189], v[180:181], v[220:221]
	v_pk_mul_f32 v[190:191], v[182:183], v[220:221]
	v_exp_f32_e32 v184, v184
	v_exp_f32_e32 v185, v185
	v_exp_f32_e32 v186, v186
	v_exp_f32_e32 v187, v187
	v_exp_f32_e32 v188, v188
	v_exp_f32_e32 v189, v189
	v_exp_f32_e32 v190, v190
	v_exp_f32_e32 v191, v191
	v_pk_add_f32 v[184:185], v[184:185], v[222:223]
	v_pk_add_f32 v[186:187], v[186:187], v[222:223]
	v_pk_add_f32 v[188:189], v[188:189], v[222:223]
	v_pk_add_f32 v[190:191], v[190:191], v[222:223]
	v_rcp_f32_e32 v184, v184
	v_rcp_f32_e32 v185, v185
	v_rcp_f32_e32 v186, v186
	v_rcp_f32_e32 v187, v187
	v_rcp_f32_e32 v188, v188
	v_rcp_f32_e32 v189, v189
	v_rcp_f32_e32 v190, v190
	v_rcp_f32_e32 v191, v191
	v_pk_mul_f32 v[184:185], v[176:177], v[184:185]
	v_pk_mul_f32 v[186:187], v[178:179], v[186:187]
	v_pk_mul_f32 v[188:189], v[180:181], v[188:189]
	v_pk_mul_f32 v[190:191], v[182:183], v[190:191]
	v_cvt_pk_bf16_f32 v192, v184, v185
	v_cvt_pk_bf16_f32 v193, v186, v187
	v_cvt_pk_bf16_f32 v194, v188, v189
	v_cvt_pk_bf16_f32 v195, v190, v191
	global_store_dwordx4 v108, v[192:195], s[52:53] sc1
	v_add_u32_e32 v108, 0x2000, v108
	s_add_i32 s56, s56, 1
	s_branch .LBB0_1544
